# SGPR-base LDS-DMA form also in MERGE and UP GEMM loops
# speedup vs baseline: 1.0009x; 1.0009x over previous
; #define PG8_STAGE(bufoff, gbase, voff) do { _Pragma("unroll") for (int _i = 0; _i < 2; ++_i) \
;         __builtin_amdgcn_global_load_lds((const unsigned*)((const char*)(gbase) + (voff)[_i]), (PG8_LAS unsigned*)(lds + (bufoff) + ldsw + _i * 8192), 16, 0, 0); } while (0)
; #define PG8_LDA(dst, b, h) do { _Pragma("unroll") for (int m = 0; m < 4; ++m) _Pragma("unroll") for (int k = 0; k < 2; ++k) dst[m][k] = *(const PG8_LAS bf16x8*)(lds + PG8_SA(b, h) + aoff + m * 2048 + k * 1024); } while (0)
; #define PG8_LDB(dst, b, h) do { _Pragma("unroll") for (int n = 0; n < 2; ++n) _Pragma("unroll") for (int k = 0; k < 2; ++k) dst[n][k] = *(const PG8_LAS bf16x8*)(lds + PG8_SB(b, h) + boff + n * 2048 + k * 1024); } while (0)
; template <class Epi, class Sched, bool ALIGN_EPI = false, bool SP2 = false>
; __device__ __forceinline__ void gemm_phase(PG8_LAS unsigned char* lds, const Gemm g, const Sched& S, const Epi& E) {
;     ...
;         for (int t = 0; t < nt; t += 2) {
;             const bool last = (t == nt - 2);
;             const char* a1 = cA + (size_t)(t + 1) * kstep;
;             const char* a2 = last ? nA : cA + (size_t)(t + 2) * kstep; const char* b2 = last ? nB : cB + (size_t)(t + 2) * kstep;
;             const char* a3 = a2 + kstep; const char* b3 = b2 + kstep;
;             if (last && has_next) S.a_ready(nxt);
;             if constexpr (SP2) {
;             PG8_LDB(B0, 0, 0); PG8_LDB(B1, 0, 1); PG8_SCHED; PG8_LDA(At, 0, 0); PG8_STAGE(PG8_SA(1, 1), a1 + hstep, voffA);
;             PG8_WAIT_V(8); PG8_WAIT_L(0); PG8_BAR; PG8_MMA(0, 0, At, B0); PG8_MMA(0, 1, At, B1); PG8_BAR; PG8_SCHED;
;             PG8_LDA(At, 0, 1); PG8_STAGE(PG8_SB(0, 0), b2, voffB); PG8_STAGE(PG8_SB(0, 1), b2 + hstep, voffB); PG8_STAGE(PG8_SA(0, 0), a2, voffA);
;             PG8_WAIT_V(8); PG8_WAIT_L(0); PG8_BAR; PG8_MMA(1, 0, At, B0); PG8_MMA(1, 1, At, B1); PG8_BAR; PG8_SCHED;
;             PG8_LDB(B0, 1, 0); PG8_LDB(B1, 1, 1); PG8_SCHED; PG8_LDA(At, 1, 0); PG8_STAGE(PG8_SA(0, 1), a2 + hstep, voffA);
;             PG8_WAIT_V(8); PG8_WAIT_L(0); PG8_BAR; PG8_MMA(0, 0, At, B0); PG8_MMA(0, 1, At, B1); PG8_BAR; PG8_SCHED;
;             PG8_LDA(At, 1, 1); PG8_STAGE(PG8_SB(1, 0), b3, voffB); PG8_STAGE(PG8_SB(1, 1), b3 + hstep, voffB); PG8_STAGE(PG8_SA(1, 0), a3, voffA);
;             PG8_WAIT_V(8); PG8_WAIT_L(0); PG8_BAR; PG8_MMA(1, 0, At, B0); PG8_MMA(1, 1, At, B1); PG8_BAR; PG8_SCHED;
.LBB0_958:
	s_sub_i32 vcc_hi, 0x29000, s100
	s_sub_i32 vcc_hi, vcc_hi, s101
	s_add_u32 s4, s26, 0xfffe0080
	s_addc_u32 s5, s27, -1
	s_add_i32 s72, 0, 0x10000
	s_cmp_eq_u32 s71, 4
	s_cselect_b32 s39, s17, s5
	s_cselect_b32 s38, s29, s4
	v_add_u32_e32 v0, s72, v242
	s_cselect_b32 s5, s19, s70
	s_cselect_b32 s4, s68, s69
	s_add_i32 s74, 0, 0x14000
	ds_read_b128 v[130:133], v0
	ds_read_b128 v[134:137], v0 offset:1024
	ds_read_b128 v[138:141], v0 offset:2048
	ds_read_b128 v[142:145], v0 offset:3072
	v_add_u32_e32 v0, s74, v242
	ds_read_b128 v[146:149], v0
	ds_read_b128 v[150:153], v0 offset:1024
	ds_read_b128 v[154:157], v0 offset:2048
	ds_read_b128 v[158:161], v0 offset:3072
	s_add_i32 m0, s58, 0xc000
	v_add_u32_e32 v250, s100, v244
	ds_read_b128 v[162:165], v250
	ds_read_b128 v[166:169], v250 offset:1024
	ds_read_b128 v[170:173], v250 offset:2048
	ds_read_b128 v[174:177], v250 offset:3072
	ds_read_b128 v[178:181], v250 offset:4096
	ds_read_b128 v[182:185], v250 offset:5120
	ds_read_b128 v[186:189], v250 offset:6144
	ds_read_b128 v[190:193], v250 offset:7168
	global_load_lds_dwordx4 v208, s[26:27]
	s_add_i32 m0, s58, 0xe000
	s_nop 0
	global_load_lds_dwordx4 v210, s[26:27]
	s_add_i32 m0, vcc_hi, s58
	s_nop 0
	global_load_lds_dwordx4 v206, s[38:39]
	s_add_i32 m0, m0, 0x2000
	s_nop 0
	global_load_lds_dwordx4 v202, s[38:39]
	s_waitcnt vmcnt(10)
	s_waitcnt lgkmcnt(0)
	s_setprio 1
	s_waitcnt lgkmcnt(0)
	v_mfma_f32_16x16x32_bf16 v[126:129], v[130:133], v[162:165], v[126:129]
	v_mfma_f32_16x16x32_bf16 v[118:121], v[138:141], v[162:165], v[118:121]
	v_mfma_f32_16x16x32_bf16 v[110:113], v[130:133], v[170:173], v[110:113]
	v_mfma_f32_16x16x32_bf16 v[102:105], v[138:141], v[170:173], v[102:105]
	s_barrier
	v_mfma_f32_16x16x32_bf16 v[94:97], v[130:133], v[178:181], v[94:97]
	v_mfma_f32_16x16x32_bf16 v[86:89], v[138:141], v[178:181], v[86:89]
	v_mfma_f32_16x16x32_bf16 v[78:81], v[130:133], v[186:189], v[78:81]
	v_mfma_f32_16x16x32_bf16 v[70:73], v[138:141], v[186:189], v[70:73]
	v_mfma_f32_16x16x32_bf16 v[126:129], v[134:137], v[166:169], v[126:129]
	v_mfma_f32_16x16x32_bf16 v[118:121], v[142:145], v[166:169], v[118:121]
	v_mfma_f32_16x16x32_bf16 v[110:113], v[134:137], v[174:177], v[110:113]
	v_mfma_f32_16x16x32_bf16 v[102:105], v[142:145], v[174:177], v[102:105]
	v_mfma_f32_16x16x32_bf16 v[94:97], v[134:137], v[182:185], v[94:97]
	v_mfma_f32_16x16x32_bf16 v[86:89], v[142:145], v[182:185], v[86:89]
	v_mfma_f32_16x16x32_bf16 v[78:81], v[134:137], v[190:193], v[78:81]
	v_mfma_f32_16x16x32_bf16 v[70:73], v[142:145], v[190:193], v[70:73]
	s_setprio 0
	s_setprio 1
	v_mfma_f32_16x16x32_bf16 v[122:125], v[146:149], v[162:165], v[122:125]
	v_mfma_f32_16x16x32_bf16 v[114:117], v[154:157], v[162:165], v[114:117]
	v_mfma_f32_16x16x32_bf16 v[106:109], v[146:149], v[170:173], v[106:109]
	v_mfma_f32_16x16x32_bf16 v[98:101], v[154:157], v[170:173], v[98:101]
	v_mfma_f32_16x16x32_bf16 v[90:93], v[146:149], v[178:181], v[90:93]
	v_mfma_f32_16x16x32_bf16 v[82:85], v[154:157], v[178:181], v[82:85]
	v_mfma_f32_16x16x32_bf16 v[74:77], v[146:149], v[186:189], v[74:77]
	v_mfma_f32_16x16x32_bf16 v[66:69], v[154:157], v[186:189], v[66:69]
	v_mfma_f32_16x16x32_bf16 v[122:125], v[150:153], v[166:169], v[122:125]
	v_mfma_f32_16x16x32_bf16 v[114:117], v[158:161], v[166:169], v[114:117]
	v_mfma_f32_16x16x32_bf16 v[106:109], v[150:153], v[174:177], v[106:109]
	v_mfma_f32_16x16x32_bf16 v[98:101], v[158:161], v[174:177], v[98:101]
	v_mfma_f32_16x16x32_bf16 v[90:93], v[150:153], v[182:185], v[90:93]
	v_mfma_f32_16x16x32_bf16 v[82:85], v[158:161], v[182:185], v[82:85]
	v_mfma_f32_16x16x32_bf16 v[74:77], v[150:153], v[190:193], v[74:77]
	v_mfma_f32_16x16x32_bf16 v[66:69], v[158:161], v[190:193], v[66:69]
	s_setprio 0
	s_barrier
	s_add_i32 s72, s72, s57
	s_mov_b32 m0, s72
	ds_read_b128 v[162:165], v244 offset:16384
	ds_read_b128 v[166:169], v244 offset:17408
	ds_read_b128 v[170:173], v244 offset:18432
	ds_read_b128 v[174:177], v244 offset:19456
	ds_read_b128 v[178:181], v244 offset:20480
	ds_read_b128 v[182:185], v244 offset:21504
	ds_read_b128 v[186:189], v244 offset:22528
	ds_read_b128 v[190:193], v244 offset:23552
	global_load_lds_dwordx4 v204, s[4:5]
	s_add_i32 m0, s72, 0x2000
	s_add_u32 s72, s4, 0x20000
	s_addc_u32 s73, s5, 0
	s_add_i32 s74, s74, s57
	global_load_lds_dwordx4 v194, s[4:5]
	s_mov_b32 m0, s74
	s_nop 0
	global_load_lds_dwordx4 v204, s[72:73]
	s_add_i32 m0, s74, 0x2000
	s_nop 0
	global_load_lds_dwordx4 v194, s[72:73]
	s_waitcnt vmcnt(8)
	s_waitcnt lgkmcnt(0)
	s_setprio 1
	s_waitcnt lgkmcnt(0)
	v_mfma_f32_16x16x32_bf16 v[62:65], v[130:133], v[162:165], v[62:65]
	v_mfma_f32_16x16x32_bf16 v[54:57], v[138:141], v[162:165], v[54:57]
	v_mfma_f32_16x16x32_bf16 v[46:49], v[130:133], v[170:173], v[46:49]
	v_mfma_f32_16x16x32_bf16 v[38:41], v[138:141], v[170:173], v[38:41]
	s_barrier
; #define PG8_STAGE(bufoff, gbase, voff) do { _Pragma("unroll") for (int _i = 0; _i < 2; ++_i) \
;         __builtin_amdgcn_global_load_lds((const unsigned*)((const char*)(gbase) + (voff)[_i]), (PG8_LAS unsigned*)(lds + (bufoff) + ldsw + _i * 8192), 16, 0, 0); } while (0)
; #define PG8_LDA(dst, b, h) do { _Pragma("unroll") for (int m = 0; m < 4; ++m) _Pragma("unroll") for (int k = 0; k < 2; ++k) dst[m][k] = *(const PG8_LAS bf16x8*)(lds + PG8_SA(b, h) + aoff + m * 2048 + k * 1024); } while (0)
; #define PG8_LDB(dst, b, h) do { _Pragma("unroll") for (int n = 0; n < 2; ++n) _Pragma("unroll") for (int k = 0; k < 2; ++k) dst[n][k] = *(const PG8_LAS bf16x8*)(lds + PG8_SB(b, h) + boff + n * 2048 + k * 1024); } while (0)
; template <class Epi, class Sched, bool ALIGN_EPI = false, bool SP2 = false>
; __device__ __forceinline__ void gemm_phase(PG8_LAS unsigned char* lds, const Gemm g, const Sched& S, const Epi& E) {
;     ...
;         for (int t = 0; t < nt; t += 2) {
;             const bool last = (t == nt - 2);
;             const char* a1 = cA + (size_t)(t + 1) * kstep;
;             const char* a2 = last ? nA : cA + (size_t)(t + 2) * kstep; const char* b2 = last ? nB : cB + (size_t)(t + 2) * kstep;
;             const char* a3 = a2 + kstep; const char* b3 = b2 + kstep;
;             if (last && has_next) S.a_ready(nxt);
;             if constexpr (SP2) {
;             PG8_LDB(B0, 0, 0); PG8_LDB(B1, 0, 1); PG8_SCHED; PG8_LDA(At, 0, 0); PG8_STAGE(PG8_SA(1, 1), a1 + hstep, voffA);
;             PG8_WAIT_V(8); PG8_WAIT_L(0); PG8_BAR; PG8_MMA(0, 0, At, B0); PG8_MMA(0, 1, At, B1); PG8_BAR; PG8_SCHED;
;             PG8_LDA(At, 0, 1); PG8_STAGE(PG8_SB(0, 0), b2, voffB); PG8_STAGE(PG8_SB(0, 1), b2 + hstep, voffB); PG8_STAGE(PG8_SA(0, 0), a2, voffA);
;             PG8_WAIT_V(8); PG8_WAIT_L(0); PG8_BAR; PG8_MMA(1, 0, At, B0); PG8_MMA(1, 1, At, B1); PG8_BAR; PG8_SCHED;
;             PG8_LDB(B0, 1, 0); PG8_LDB(B1, 1, 1); PG8_SCHED; PG8_LDA(At, 1, 0); PG8_STAGE(PG8_SA(0, 1), a2 + hstep, voffA);
;             PG8_WAIT_V(8); PG8_WAIT_L(0); PG8_BAR; PG8_MMA(0, 0, At, B0); PG8_MMA(0, 1, At, B1); PG8_BAR; PG8_SCHED;
;             PG8_LDA(At, 1, 1); PG8_STAGE(PG8_SB(1, 0), b3, voffB); PG8_STAGE(PG8_SB(1, 1), b3 + hstep, voffB); PG8_STAGE(PG8_SA(1, 0), a3, voffA);
;             PG8_WAIT_V(8); PG8_WAIT_L(0); PG8_BAR; PG8_MMA(1, 0, At, B0); PG8_MMA(1, 1, At, B1); PG8_BAR; PG8_SCHED;
	v_mfma_f32_16x16x32_bf16 v[30:33], v[130:133], v[178:181], v[30:33]
	v_mfma_f32_16x16x32_bf16 v[22:25], v[138:141], v[178:181], v[22:25]
	v_mfma_f32_16x16x32_bf16 v[14:17], v[130:133], v[186:189], v[14:17]
	v_mfma_f32_16x16x32_bf16 v[6:9], v[138:141], v[186:189], v[6:9]
	v_mfma_f32_16x16x32_bf16 v[62:65], v[134:137], v[166:169], v[62:65]
	v_mfma_f32_16x16x32_bf16 v[54:57], v[142:145], v[166:169], v[54:57]
	v_mfma_f32_16x16x32_bf16 v[46:49], v[134:137], v[174:177], v[46:49]
	v_mfma_f32_16x16x32_bf16 v[38:41], v[142:145], v[174:177], v[38:41]
	v_mfma_f32_16x16x32_bf16 v[30:33], v[134:137], v[182:185], v[30:33]
	v_mfma_f32_16x16x32_bf16 v[22:25], v[142:145], v[182:185], v[22:25]
	v_mfma_f32_16x16x32_bf16 v[14:17], v[134:137], v[190:193], v[14:17]
	v_mfma_f32_16x16x32_bf16 v[6:9], v[142:145], v[190:193], v[6:9]
	s_setprio 0
	s_setprio 1
	v_mfma_f32_16x16x32_bf16 v[58:61], v[146:149], v[162:165], v[58:61]
	v_mfma_f32_16x16x32_bf16 v[50:53], v[154:157], v[162:165], v[50:53]
	v_mfma_f32_16x16x32_bf16 v[42:45], v[146:149], v[170:173], v[42:45]
	v_mfma_f32_16x16x32_bf16 v[34:37], v[154:157], v[170:173], v[34:37]
	v_mfma_f32_16x16x32_bf16 v[26:29], v[146:149], v[178:181], v[26:29]
	v_mfma_f32_16x16x32_bf16 v[18:21], v[154:157], v[178:181], v[18:21]
	v_mfma_f32_16x16x32_bf16 v[10:13], v[146:149], v[186:189], v[10:13]
	v_mfma_f32_16x16x32_bf16 v[2:5], v[154:157], v[186:189], v[2:5]
	v_mfma_f32_16x16x32_bf16 v[58:61], v[150:153], v[166:169], v[58:61]
	v_mfma_f32_16x16x32_bf16 v[50:53], v[158:161], v[166:169], v[50:53]
	v_mfma_f32_16x16x32_bf16 v[42:45], v[150:153], v[174:177], v[42:45]
	v_mfma_f32_16x16x32_bf16 v[34:37], v[158:161], v[174:177], v[34:37]
	v_mfma_f32_16x16x32_bf16 v[26:29], v[150:153], v[182:185], v[26:29]
	v_mfma_f32_16x16x32_bf16 v[18:21], v[158:161], v[182:185], v[18:21]
	v_mfma_f32_16x16x32_bf16 v[10:13], v[150:153], v[190:193], v[10:13]
	v_mfma_f32_16x16x32_bf16 v[2:5], v[158:161], v[190:193], v[2:5]
	s_setprio 0
	s_barrier
	s_add_i32 s72, 0, 0x18000
	v_add_u32_e32 v0, s72, v242
	s_add_i32 s73, 0, 0x1c000
	ds_read_b128 v[130:133], v0
	ds_read_b128 v[134:137], v0 offset:1024
	ds_read_b128 v[138:141], v0 offset:2048
	ds_read_b128 v[142:145], v0 offset:3072
	v_add_u32_e32 v0, s73, v242
	ds_read_b128 v[146:149], v0
	ds_read_b128 v[150:153], v0 offset:1024
	ds_read_b128 v[154:157], v0 offset:2048
	ds_read_b128 v[158:161], v0 offset:3072
	s_add_u32 s38, s38, 0x20000
	s_addc_u32 s39, s39, 0
	s_mov_b32 m0, s60
	v_add_u32_e32 v250, s101, v244
	ds_read_b128 v[162:165], v250
	ds_read_b128 v[166:169], v250 offset:1024
	ds_read_b128 v[170:173], v250 offset:2048
	ds_read_b128 v[174:177], v250 offset:3072
	ds_read_b128 v[178:181], v250 offset:4096
	ds_read_b128 v[182:185], v250 offset:5120
	ds_read_b128 v[186:189], v250 offset:6144
	ds_read_b128 v[190:193], v250 offset:7168
	global_load_lds_dwordx4 v206, s[38:39]
	s_mov_b32 m0, s61
	s_nop 0
	global_load_lds_dwordx4 v202, s[38:39]
	s_sub_u32 s38, s38, 0x1ff80
	s_subb_u32 s39, s39, 0
	s_add_i32 m0, s100, s58
	s_nop 0
	global_load_lds_dwordx4 v206, s[38:39]
	s_add_i32 m0, m0, 0x2000
	s_nop 0
	global_load_lds_dwordx4 v202, s[38:39]
	s_waitcnt vmcnt(10)
	s_waitcnt lgkmcnt(0)
	s_setprio 1
	s_waitcnt lgkmcnt(0)
	v_mfma_f32_16x16x32_bf16 v[126:129], v[130:133], v[162:165], v[126:129]
	v_mfma_f32_16x16x32_bf16 v[118:121], v[138:141], v[162:165], v[118:121]
	v_mfma_f32_16x16x32_bf16 v[110:113], v[130:133], v[170:173], v[110:113]
	v_mfma_f32_16x16x32_bf16 v[102:105], v[138:141], v[170:173], v[102:105]
	s_barrier
; #define PG8_STAGE(bufoff, gbase, voff) do { _Pragma("unroll") for (int _i = 0; _i < 2; ++_i) \
;         __builtin_amdgcn_global_load_lds((const unsigned*)((const char*)(gbase) + (voff)[_i]), (PG8_LAS unsigned*)(lds + (bufoff) + ldsw + _i * 8192), 16, 0, 0); } while (0)
; #define PG8_LDA(dst, b, h) do { _Pragma("unroll") for (int m = 0; m < 4; ++m) _Pragma("unroll") for (int k = 0; k < 2; ++k) dst[m][k] = *(const PG8_LAS bf16x8*)(lds + PG8_SA(b, h) + aoff + m * 2048 + k * 1024); } while (0)
; #define PG8_LDB(dst, b, h) do { _Pragma("unroll") for (int n = 0; n < 2; ++n) _Pragma("unroll") for (int k = 0; k < 2; ++k) dst[n][k] = *(const PG8_LAS bf16x8*)(lds + PG8_SB(b, h) + boff + n * 2048 + k * 1024); } while (0)
; template <class Epi, class Sched, bool ALIGN_EPI = false, bool SP2 = false>
; __device__ __forceinline__ void gemm_phase(PG8_LAS unsigned char* lds, const Gemm g, const Sched& S, const Epi& E) {
;     ...
;         for (int t = 0; t < nt; t += 2) {
;             const bool last = (t == nt - 2);
;             const char* a1 = cA + (size_t)(t + 1) * kstep;
;             const char* a2 = last ? nA : cA + (size_t)(t + 2) * kstep; const char* b2 = last ? nB : cB + (size_t)(t + 2) * kstep;
;             const char* a3 = a2 + kstep; const char* b3 = b2 + kstep;
;             if (last && has_next) S.a_ready(nxt);
;             if constexpr (SP2) {
;             PG8_LDB(B0, 0, 0); PG8_LDB(B1, 0, 1); PG8_SCHED; PG8_LDA(At, 0, 0); PG8_STAGE(PG8_SA(1, 1), a1 + hstep, voffA);
;             PG8_WAIT_V(8); PG8_WAIT_L(0); PG8_BAR; PG8_MMA(0, 0, At, B0); PG8_MMA(0, 1, At, B1); PG8_BAR; PG8_SCHED;
;             PG8_LDA(At, 0, 1); PG8_STAGE(PG8_SB(0, 0), b2, voffB); PG8_STAGE(PG8_SB(0, 1), b2 + hstep, voffB); PG8_STAGE(PG8_SA(0, 0), a2, voffA);
;             PG8_WAIT_V(8); PG8_WAIT_L(0); PG8_BAR; PG8_MMA(1, 0, At, B0); PG8_MMA(1, 1, At, B1); PG8_BAR; PG8_SCHED;
;             PG8_LDB(B0, 1, 0); PG8_LDB(B1, 1, 1); PG8_SCHED; PG8_LDA(At, 1, 0); PG8_STAGE(PG8_SA(0, 1), a2 + hstep, voffA);
;             PG8_WAIT_V(8); PG8_WAIT_L(0); PG8_BAR; PG8_MMA(0, 0, At, B0); PG8_MMA(0, 1, At, B1); PG8_BAR; PG8_SCHED;
;             PG8_LDA(At, 1, 1); PG8_STAGE(PG8_SB(1, 0), b3, voffB); PG8_STAGE(PG8_SB(1, 1), b3 + hstep, voffB); PG8_STAGE(PG8_SA(1, 0), a3, voffA);
;             PG8_WAIT_V(8); PG8_WAIT_L(0); PG8_BAR; PG8_MMA(1, 0, At, B0); PG8_MMA(1, 1, At, B1); PG8_BAR; PG8_SCHED;
	v_mfma_f32_16x16x32_bf16 v[94:97], v[130:133], v[178:181], v[94:97]
	v_mfma_f32_16x16x32_bf16 v[86:89], v[138:141], v[178:181], v[86:89]
	v_mfma_f32_16x16x32_bf16 v[78:81], v[130:133], v[186:189], v[78:81]
	v_mfma_f32_16x16x32_bf16 v[70:73], v[138:141], v[186:189], v[70:73]
	v_mfma_f32_16x16x32_bf16 v[126:129], v[134:137], v[166:169], v[126:129]
	v_mfma_f32_16x16x32_bf16 v[118:121], v[142:145], v[166:169], v[118:121]
	v_mfma_f32_16x16x32_bf16 v[110:113], v[134:137], v[174:177], v[110:113]
	v_mfma_f32_16x16x32_bf16 v[102:105], v[142:145], v[174:177], v[102:105]
	v_mfma_f32_16x16x32_bf16 v[94:97], v[134:137], v[182:185], v[94:97]
	v_mfma_f32_16x16x32_bf16 v[86:89], v[142:145], v[182:185], v[86:89]
	v_mfma_f32_16x16x32_bf16 v[78:81], v[134:137], v[190:193], v[78:81]
	v_mfma_f32_16x16x32_bf16 v[70:73], v[142:145], v[190:193], v[70:73]
	s_setprio 0
	s_setprio 1
	v_mfma_f32_16x16x32_bf16 v[122:125], v[146:149], v[162:165], v[122:125]
	v_mfma_f32_16x16x32_bf16 v[114:117], v[154:157], v[162:165], v[114:117]
	v_mfma_f32_16x16x32_bf16 v[106:109], v[146:149], v[170:173], v[106:109]
	v_mfma_f32_16x16x32_bf16 v[98:101], v[154:157], v[170:173], v[98:101]
	v_mfma_f32_16x16x32_bf16 v[90:93], v[146:149], v[178:181], v[90:93]
	v_mfma_f32_16x16x32_bf16 v[82:85], v[154:157], v[178:181], v[82:85]
	v_mfma_f32_16x16x32_bf16 v[74:77], v[146:149], v[186:189], v[74:77]
	v_mfma_f32_16x16x32_bf16 v[66:69], v[154:157], v[186:189], v[66:69]
	v_mfma_f32_16x16x32_bf16 v[122:125], v[150:153], v[166:169], v[122:125]
	v_mfma_f32_16x16x32_bf16 v[114:117], v[158:161], v[166:169], v[114:117]
	v_mfma_f32_16x16x32_bf16 v[106:109], v[150:153], v[174:177], v[106:109]
	v_mfma_f32_16x16x32_bf16 v[98:101], v[158:161], v[174:177], v[98:101]
	v_mfma_f32_16x16x32_bf16 v[90:93], v[150:153], v[182:185], v[90:93]
	v_mfma_f32_16x16x32_bf16 v[82:85], v[158:161], v[182:185], v[82:85]
	v_mfma_f32_16x16x32_bf16 v[74:77], v[150:153], v[190:193], v[74:77]
	v_mfma_f32_16x16x32_bf16 v[66:69], v[158:161], v[190:193], v[66:69]
	s_setprio 0
	s_barrier
	s_add_i32 s38, s72, s57
	s_mov_b32 m0, s38
	ds_read_b128 v[162:165], v244 offset:49152
	ds_read_b128 v[166:169], v244 offset:50176
	ds_read_b128 v[170:173], v244 offset:51200
	ds_read_b128 v[174:177], v244 offset:52224
	ds_read_b128 v[178:181], v244 offset:53248
	ds_read_b128 v[182:185], v244 offset:54272
	ds_read_b128 v[186:189], v244 offset:55296
	ds_read_b128 v[190:193], v244 offset:56320
	s_add_u32 s4, s4, 0x80
	s_addc_u32 s5, s5, 0
	global_load_lds_dwordx4 v204, s[4:5]
	s_add_i32 m0, s38, 0x2000
	s_add_i32 s38, s73, s57
	global_load_lds_dwordx4 v194, s[4:5]
	s_add_u32 s4, s4, 0x20000
	s_addc_u32 s5, s5, 0
	s_mov_b32 m0, s38
	s_nop 0
	global_load_lds_dwordx4 v204, s[4:5]
	s_add_i32 m0, s38, 0x2000
	s_nop 0
	global_load_lds_dwordx4 v194, s[4:5]
	s_waitcnt vmcnt(8)
	s_waitcnt lgkmcnt(0)
	s_setprio 1
	s_waitcnt lgkmcnt(0)
	v_mfma_f32_16x16x32_bf16 v[62:65], v[130:133], v[162:165], v[62:65]
	v_mfma_f32_16x16x32_bf16 v[54:57], v[138:141], v[162:165], v[54:57]
	v_mfma_f32_16x16x32_bf16 v[46:49], v[130:133], v[170:173], v[46:49]
	v_mfma_f32_16x16x32_bf16 v[38:41], v[138:141], v[170:173], v[38:41]
	s_barrier
	v_mfma_f32_16x16x32_bf16 v[30:33], v[130:133], v[178:181], v[30:33]
	v_mfma_f32_16x16x32_bf16 v[22:25], v[138:141], v[178:181], v[22:25]
	v_mfma_f32_16x16x32_bf16 v[14:17], v[130:133], v[186:189], v[14:17]
	v_mfma_f32_16x16x32_bf16 v[6:9], v[138:141], v[186:189], v[6:9]
	v_mfma_f32_16x16x32_bf16 v[62:65], v[134:137], v[166:169], v[62:65]
	v_mfma_f32_16x16x32_bf16 v[54:57], v[142:145], v[166:169], v[54:57]
	v_mfma_f32_16x16x32_bf16 v[46:49], v[134:137], v[174:177], v[46:49]
	v_mfma_f32_16x16x32_bf16 v[38:41], v[142:145], v[174:177], v[38:41]
	v_mfma_f32_16x16x32_bf16 v[30:33], v[134:137], v[182:185], v[30:33]
	v_mfma_f32_16x16x32_bf16 v[22:25], v[142:145], v[182:185], v[22:25]
	v_mfma_f32_16x16x32_bf16 v[14:17], v[134:137], v[190:193], v[14:17]
	v_mfma_f32_16x16x32_bf16 v[6:9], v[142:145], v[190:193], v[6:9]
	s_setprio 0
	s_setprio 1
	v_mfma_f32_16x16x32_bf16 v[58:61], v[146:149], v[162:165], v[58:61]
	v_mfma_f32_16x16x32_bf16 v[50:53], v[154:157], v[162:165], v[50:53]
	v_mfma_f32_16x16x32_bf16 v[42:45], v[146:149], v[170:173], v[42:45]
	v_mfma_f32_16x16x32_bf16 v[34:37], v[154:157], v[170:173], v[34:37]
	v_mfma_f32_16x16x32_bf16 v[26:29], v[146:149], v[178:181], v[26:29]
	v_mfma_f32_16x16x32_bf16 v[18:21], v[154:157], v[178:181], v[18:21]
	v_mfma_f32_16x16x32_bf16 v[10:13], v[146:149], v[186:189], v[10:13]
	v_mfma_f32_16x16x32_bf16 v[2:5], v[154:157], v[186:189], v[2:5]
	v_mfma_f32_16x16x32_bf16 v[58:61], v[150:153], v[166:169], v[58:61]
	v_mfma_f32_16x16x32_bf16 v[50:53], v[158:161], v[166:169], v[50:53]
	v_mfma_f32_16x16x32_bf16 v[42:45], v[150:153], v[174:177], v[42:45]
	v_mfma_f32_16x16x32_bf16 v[34:37], v[158:161], v[174:177], v[34:37]
	v_mfma_f32_16x16x32_bf16 v[26:29], v[150:153], v[182:185], v[26:29]
	v_mfma_f32_16x16x32_bf16 v[18:21], v[158:161], v[182:185], v[18:21]
	v_mfma_f32_16x16x32_bf16 v[10:13], v[150:153], v[190:193], v[10:13]
	v_mfma_f32_16x16x32_bf16 v[2:5], v[158:161], v[190:193], v[2:5]
	s_setprio 0
	s_barrier
	s_add_i32 s71, s71, 2
	s_mov_b32 s101, s100
	s_mov_b32 s100, vcc_hi
	s_add_u32 s26, s26, 0x100
	s_addc_u32 s27, s27, 0
	s_add_u32 s69, s69, 0x100
	s_addc_u32 s70, s70, 0
	s_cmp_gt_u32 s71, 5
	s_cbranch_scc0 .LBB0_958
	s_and_b64 vcc, exec, s[14:15]
	s_cbranch_vccz .LBB0_961
	s_barrier

; #define PG8_STAGE(bufoff, gbase, voff) do { _Pragma("unroll") for (int _i = 0; _i < 2; ++_i) \
;         __builtin_amdgcn_global_load_lds((const unsigned*)((const char*)(gbase) + (voff)[_i]), (PG8_LAS unsigned*)(lds + (bufoff) + ldsw + _i * 8192), 16, 0, 0); } while (0)
; #define PG8_LDA(dst, b, h) do { _Pragma("unroll") for (int m = 0; m < 4; ++m) _Pragma("unroll") for (int k = 0; k < 2; ++k) dst[m][k] = *(const PG8_LAS bf16x8*)(lds + PG8_SA(b, h) + aoff + m * 2048 + k * 1024); } while (0)
; #define PG8_LDB(dst, b, h) do { _Pragma("unroll") for (int n = 0; n < 2; ++n) _Pragma("unroll") for (int k = 0; k < 2; ++k) dst[n][k] = *(const PG8_LAS bf16x8*)(lds + PG8_SB(b, h) + boff + n * 2048 + k * 1024); } while (0)
; template <class Epi, class Sched, bool ALIGN_EPI = false, bool SP2 = false>
; __device__ __forceinline__ void gemm_phase(PG8_LAS unsigned char* lds, const Gemm g, const Sched& S, const Epi& E) {
;     ...
;         for (int t = 0; t < nt; t += 2) {
;             const bool last = (t == nt - 2);
;             const char* a1 = cA + (size_t)(t + 1) * kstep;
;             const char* a2 = last ? nA : cA + (size_t)(t + 2) * kstep; const char* b2 = last ? nB : cB + (size_t)(t + 2) * kstep;
;             const char* a3 = a2 + kstep; const char* b3 = b2 + kstep;
;             if (last && has_next) S.a_ready(nxt);
;             if constexpr (SP2) {
;             PG8_LDB(B0, 0, 0); PG8_LDB(B1, 0, 1); PG8_SCHED; PG8_LDA(At, 0, 0); PG8_STAGE(PG8_SA(1, 1), a1 + hstep, voffA);
;             PG8_WAIT_V(8); PG8_WAIT_L(0); PG8_BAR; PG8_MMA(0, 0, At, B0); PG8_MMA(0, 1, At, B1); PG8_BAR; PG8_SCHED;
;             PG8_LDA(At, 0, 1); PG8_STAGE(PG8_SB(0, 0), b2, voffB); PG8_STAGE(PG8_SB(0, 1), b2 + hstep, voffB); PG8_STAGE(PG8_SA(0, 0), a2, voffA);
;             PG8_WAIT_V(8); PG8_WAIT_L(0); PG8_BAR; PG8_MMA(1, 0, At, B0); PG8_MMA(1, 1, At, B1); PG8_BAR; PG8_SCHED;
;             PG8_LDB(B0, 1, 0); PG8_LDB(B1, 1, 1); PG8_SCHED; PG8_LDA(At, 1, 0); PG8_STAGE(PG8_SA(0, 1), a2 + hstep, voffA);
;             PG8_WAIT_V(8); PG8_WAIT_L(0); PG8_BAR; PG8_MMA(0, 0, At, B0); PG8_MMA(0, 1, At, B1); PG8_BAR; PG8_SCHED;
;             PG8_LDA(At, 1, 1); PG8_STAGE(PG8_SB(1, 0), b3, voffB); PG8_STAGE(PG8_SB(1, 1), b3 + hstep, voffB); PG8_STAGE(PG8_SA(1, 0), a3, voffA);
;             PG8_WAIT_V(8); PG8_WAIT_L(0); PG8_BAR; PG8_MMA(1, 0, At, B0); PG8_MMA(1, 1, At, B1); PG8_BAR; PG8_SCHED;
.LBB0_1423:
	s_sub_i32 vcc_hi, 0x29000, s100
	s_sub_i32 vcc_hi, vcc_hi, s101
	s_add_u32 s61, s64, 0xfff80080
	s_addc_u32 s62, s65, -1
	s_add_i32 s85, 0, 0x10000
	s_cmp_eq_u32 s59, 28
	s_cselect_b32 s67, s0, s62
	s_cselect_b32 s66, s1, s61
	s_cselect_b32 s63, s28, s53
	s_cselect_b32 s62, s29, s51
	s_add_i32 s61, 0, 0x14000
	v_add_u32_e32 v142, s85, v169
	v_add_u32_e32 v158, s61, v169
	ds_read_b128 v[130:133], v142
	ds_read_b128 v[134:137], v142 offset:1024
	ds_read_b128 v[138:141], v142 offset:2048
	ds_read_b128 v[142:145], v142 offset:3072
	ds_read_b128 v[146:149], v158
	ds_read_b128 v[150:153], v158 offset:1024
	ds_read_b128 v[154:157], v158 offset:2048
	ds_read_b128 v[158:161], v158 offset:3072
	s_add_i32 m0, s77, 0xc000
	v_add_u32_e32 v250, s100, v208
	ds_read_b128 v[176:179], v250
	ds_read_b128 v[180:183], v250 offset:1024
	ds_read_b128 v[184:187], v250 offset:2048
	ds_read_b128 v[188:191], v250 offset:3072
	ds_read_b128 v[192:195], v250 offset:4096
	ds_read_b128 v[210:213], v250 offset:5120
	ds_read_b128 v[214:217], v250 offset:6144
	ds_read_b128 v[218:221], v250 offset:7168
	global_load_lds_dwordx4 v172, s[64:65]
	s_add_i32 m0, s77, 0xe000
	s_nop 0
	global_load_lds_dwordx4 v174, s[64:65]
	s_add_i32 m0, vcc_hi, s77
	s_nop 0
	global_load_lds_dwordx4 v162, s[66:67]
	s_add_i32 m0, m0, 0x2000
	s_nop 0
	global_load_lds_dwordx4 v164, s[66:67]
	s_waitcnt vmcnt(10)
	s_waitcnt lgkmcnt(0)
	s_setprio 1
	s_waitcnt lgkmcnt(0)
	v_mfma_f32_16x16x32_bf16 v[122:125], v[130:133], v[176:179], v[122:125]
	v_mfma_f32_16x16x32_bf16 v[58:61], v[138:141], v[176:179], v[58:61]
	v_mfma_f32_16x16x32_bf16 v[114:117], v[130:133], v[184:187], v[114:117]
	v_mfma_f32_16x16x32_bf16 v[50:53], v[138:141], v[184:187], v[50:53]
	s_barrier
	v_mfma_f32_16x16x32_bf16 v[106:109], v[130:133], v[192:195], v[106:109]
	v_mfma_f32_16x16x32_bf16 v[42:45], v[138:141], v[192:195], v[42:45]
	v_mfma_f32_16x16x32_bf16 v[98:101], v[130:133], v[214:217], v[98:101]
	v_mfma_f32_16x16x32_bf16 v[34:37], v[138:141], v[214:217], v[34:37]
	v_mfma_f32_16x16x32_bf16 v[122:125], v[134:137], v[180:183], v[122:125]
	v_mfma_f32_16x16x32_bf16 v[58:61], v[142:145], v[180:183], v[58:61]
	v_mfma_f32_16x16x32_bf16 v[114:117], v[134:137], v[188:191], v[114:117]
	v_mfma_f32_16x16x32_bf16 v[50:53], v[142:145], v[188:191], v[50:53]
	v_mfma_f32_16x16x32_bf16 v[106:109], v[134:137], v[210:213], v[106:109]
	v_mfma_f32_16x16x32_bf16 v[42:45], v[142:145], v[210:213], v[42:45]
	v_mfma_f32_16x16x32_bf16 v[98:101], v[134:137], v[218:221], v[98:101]
	v_mfma_f32_16x16x32_bf16 v[34:37], v[142:145], v[218:221], v[34:37]
	s_setprio 0
	s_setprio 1
	v_mfma_f32_16x16x32_bf16 v[126:129], v[146:149], v[176:179], v[126:129]
	v_mfma_f32_16x16x32_bf16 v[62:65], v[154:157], v[176:179], v[62:65]
	v_mfma_f32_16x16x32_bf16 v[118:121], v[146:149], v[184:187], v[118:121]
	v_mfma_f32_16x16x32_bf16 v[54:57], v[154:157], v[184:187], v[54:57]
	v_mfma_f32_16x16x32_bf16 v[110:113], v[146:149], v[192:195], v[110:113]
	v_mfma_f32_16x16x32_bf16 v[46:49], v[154:157], v[192:195], v[46:49]
	v_mfma_f32_16x16x32_bf16 v[102:105], v[146:149], v[214:217], v[102:105]
	v_mfma_f32_16x16x32_bf16 v[38:41], v[154:157], v[214:217], v[38:41]
	v_mfma_f32_16x16x32_bf16 v[126:129], v[150:153], v[180:183], v[126:129]
	v_mfma_f32_16x16x32_bf16 v[62:65], v[158:161], v[180:183], v[62:65]
	v_mfma_f32_16x16x32_bf16 v[118:121], v[150:153], v[188:191], v[118:121]
	v_mfma_f32_16x16x32_bf16 v[54:57], v[158:161], v[188:191], v[54:57]
	v_mfma_f32_16x16x32_bf16 v[110:113], v[150:153], v[210:213], v[110:113]
	v_mfma_f32_16x16x32_bf16 v[46:49], v[158:161], v[210:213], v[46:49]
	v_mfma_f32_16x16x32_bf16 v[102:105], v[150:153], v[218:221], v[102:105]
	v_mfma_f32_16x16x32_bf16 v[38:41], v[158:161], v[218:221], v[38:41]
	s_setprio 0
	s_barrier
	s_add_i32 s85, s85, s76
	s_mov_b32 m0, s85
	ds_read_b128 v[176:179], v208 offset:16384
	ds_read_b128 v[180:183], v208 offset:17408
	ds_read_b128 v[184:187], v208 offset:18432
	ds_read_b128 v[188:191], v208 offset:19456
	ds_read_b128 v[192:195], v208 offset:20480
	ds_read_b128 v[210:213], v208 offset:21504
	ds_read_b128 v[214:217], v208 offset:22528
	ds_read_b128 v[218:221], v208 offset:23552
	global_load_lds_dwordx4 v0, s[62:63]
	s_add_i32 m0, s85, 0x2000
	s_add_u32 s86, s62, 0x80000
	s_addc_u32 s87, s63, 0
	s_add_i32 s61, s61, s76
	global_load_lds_dwordx4 v166, s[62:63]
	s_mov_b32 m0, s61
	s_nop 0
	global_load_lds_dwordx4 v0, s[86:87]
	s_add_i32 m0, s61, 0x2000
	s_nop 0
	global_load_lds_dwordx4 v166, s[86:87]
	s_waitcnt vmcnt(8)
	s_waitcnt lgkmcnt(0)
	s_setprio 1
	s_waitcnt lgkmcnt(0)
	v_mfma_f32_16x16x32_bf16 v[90:93], v[130:133], v[176:179], v[90:93]
	v_mfma_f32_16x16x32_bf16 v[26:29], v[138:141], v[176:179], v[26:29]
	v_mfma_f32_16x16x32_bf16 v[82:85], v[130:133], v[184:187], v[82:85]
	v_mfma_f32_16x16x32_bf16 v[18:21], v[138:141], v[184:187], v[18:21]
	s_barrier
; #define PG8_STAGE(bufoff, gbase, voff) do { _Pragma("unroll") for (int _i = 0; _i < 2; ++_i) \
;         __builtin_amdgcn_global_load_lds((const unsigned*)((const char*)(gbase) + (voff)[_i]), (PG8_LAS unsigned*)(lds + (bufoff) + ldsw + _i * 8192), 16, 0, 0); } while (0)
; #define PG8_LDA(dst, b, h) do { _Pragma("unroll") for (int m = 0; m < 4; ++m) _Pragma("unroll") for (int k = 0; k < 2; ++k) dst[m][k] = *(const PG8_LAS bf16x8*)(lds + PG8_SA(b, h) + aoff + m * 2048 + k * 1024); } while (0)
; #define PG8_LDB(dst, b, h) do { _Pragma("unroll") for (int n = 0; n < 2; ++n) _Pragma("unroll") for (int k = 0; k < 2; ++k) dst[n][k] = *(const PG8_LAS bf16x8*)(lds + PG8_SB(b, h) + boff + n * 2048 + k * 1024); } while (0)
; template <class Epi, class Sched, bool ALIGN_EPI = false, bool SP2 = false>
; __device__ __forceinline__ void gemm_phase(PG8_LAS unsigned char* lds, const Gemm g, const Sched& S, const Epi& E) {
;     ...
;         for (int t = 0; t < nt; t += 2) {
;             const bool last = (t == nt - 2);
;             const char* a1 = cA + (size_t)(t + 1) * kstep;
;             const char* a2 = last ? nA : cA + (size_t)(t + 2) * kstep; const char* b2 = last ? nB : cB + (size_t)(t + 2) * kstep;
;             const char* a3 = a2 + kstep; const char* b3 = b2 + kstep;
;             if (last && has_next) S.a_ready(nxt);
;             if constexpr (SP2) {
;             PG8_LDB(B0, 0, 0); PG8_LDB(B1, 0, 1); PG8_SCHED; PG8_LDA(At, 0, 0); PG8_STAGE(PG8_SA(1, 1), a1 + hstep, voffA);
;             PG8_WAIT_V(8); PG8_WAIT_L(0); PG8_BAR; PG8_MMA(0, 0, At, B0); PG8_MMA(0, 1, At, B1); PG8_BAR; PG8_SCHED;
;             PG8_LDA(At, 0, 1); PG8_STAGE(PG8_SB(0, 0), b2, voffB); PG8_STAGE(PG8_SB(0, 1), b2 + hstep, voffB); PG8_STAGE(PG8_SA(0, 0), a2, voffA);
;             PG8_WAIT_V(8); PG8_WAIT_L(0); PG8_BAR; PG8_MMA(1, 0, At, B0); PG8_MMA(1, 1, At, B1); PG8_BAR; PG8_SCHED;
;             PG8_LDB(B0, 1, 0); PG8_LDB(B1, 1, 1); PG8_SCHED; PG8_LDA(At, 1, 0); PG8_STAGE(PG8_SA(0, 1), a2 + hstep, voffA);
;             PG8_WAIT_V(8); PG8_WAIT_L(0); PG8_BAR; PG8_MMA(0, 0, At, B0); PG8_MMA(0, 1, At, B1); PG8_BAR; PG8_SCHED;
;             PG8_LDA(At, 1, 1); PG8_STAGE(PG8_SB(1, 0), b3, voffB); PG8_STAGE(PG8_SB(1, 1), b3 + hstep, voffB); PG8_STAGE(PG8_SA(1, 0), a3, voffA);
;             PG8_WAIT_V(8); PG8_WAIT_L(0); PG8_BAR; PG8_MMA(1, 0, At, B0); PG8_MMA(1, 1, At, B1); PG8_BAR; PG8_SCHED;
	v_mfma_f32_16x16x32_bf16 v[74:77], v[130:133], v[192:195], v[74:77]
	v_mfma_f32_16x16x32_bf16 v[10:13], v[138:141], v[192:195], v[10:13]
	v_mfma_f32_16x16x32_bf16 v[66:69], v[130:133], v[214:217], v[66:69]
	v_mfma_f32_16x16x32_bf16 v[2:5], v[138:141], v[214:217], v[2:5]
	v_mfma_f32_16x16x32_bf16 v[90:93], v[134:137], v[180:183], v[90:93]
	v_mfma_f32_16x16x32_bf16 v[26:29], v[142:145], v[180:183], v[26:29]
	v_mfma_f32_16x16x32_bf16 v[82:85], v[134:137], v[188:191], v[82:85]
	v_mfma_f32_16x16x32_bf16 v[18:21], v[142:145], v[188:191], v[18:21]
	v_mfma_f32_16x16x32_bf16 v[74:77], v[134:137], v[210:213], v[74:77]
	v_mfma_f32_16x16x32_bf16 v[10:13], v[142:145], v[210:213], v[10:13]
	v_mfma_f32_16x16x32_bf16 v[66:69], v[134:137], v[218:221], v[66:69]
	v_mfma_f32_16x16x32_bf16 v[2:5], v[142:145], v[218:221], v[2:5]
	s_setprio 0
	s_setprio 1
	v_mfma_f32_16x16x32_bf16 v[94:97], v[146:149], v[176:179], v[94:97]
	v_mfma_f32_16x16x32_bf16 v[30:33], v[154:157], v[176:179], v[30:33]
	v_mfma_f32_16x16x32_bf16 v[86:89], v[146:149], v[184:187], v[86:89]
	v_mfma_f32_16x16x32_bf16 v[22:25], v[154:157], v[184:187], v[22:25]
	v_mfma_f32_16x16x32_bf16 v[78:81], v[146:149], v[192:195], v[78:81]
	v_mfma_f32_16x16x32_bf16 v[14:17], v[154:157], v[192:195], v[14:17]
	v_mfma_f32_16x16x32_bf16 v[70:73], v[146:149], v[214:217], v[70:73]
	v_mfma_f32_16x16x32_bf16 v[6:9], v[154:157], v[214:217], v[6:9]
	v_mfma_f32_16x16x32_bf16 v[94:97], v[150:153], v[180:183], v[94:97]
	v_mfma_f32_16x16x32_bf16 v[30:33], v[158:161], v[180:183], v[30:33]
	v_mfma_f32_16x16x32_bf16 v[86:89], v[150:153], v[188:191], v[86:89]
	v_mfma_f32_16x16x32_bf16 v[22:25], v[158:161], v[188:191], v[22:25]
	v_mfma_f32_16x16x32_bf16 v[78:81], v[150:153], v[210:213], v[78:81]
	v_mfma_f32_16x16x32_bf16 v[14:17], v[158:161], v[210:213], v[14:17]
	v_mfma_f32_16x16x32_bf16 v[70:73], v[150:153], v[218:221], v[70:73]
	v_mfma_f32_16x16x32_bf16 v[6:9], v[158:161], v[218:221], v[6:9]
	s_setprio 0
	s_barrier
	s_add_i32 s61, 0, 0x18000
	s_add_i32 s85, 0, 0x1c000
	v_add_u32_e32 v142, s61, v169
	v_add_u32_e32 v158, s85, v169
	ds_read_b128 v[130:133], v142
	ds_read_b128 v[134:137], v142 offset:1024
	ds_read_b128 v[138:141], v142 offset:2048
	ds_read_b128 v[142:145], v142 offset:3072
	ds_read_b128 v[146:149], v158
	ds_read_b128 v[150:153], v158 offset:1024
	ds_read_b128 v[154:157], v158 offset:2048
	ds_read_b128 v[158:161], v158 offset:3072
	s_add_u32 s66, s66, 0x80000
	s_addc_u32 s67, s67, 0
	s_mov_b32 m0, s79
	v_add_u32_e32 v250, s101, v208
	ds_read_b128 v[176:179], v250
	ds_read_b128 v[180:183], v250 offset:1024
	ds_read_b128 v[184:187], v250 offset:2048
	ds_read_b128 v[188:191], v250 offset:3072
	ds_read_b128 v[192:195], v250 offset:4096
	ds_read_b128 v[210:213], v250 offset:5120
	ds_read_b128 v[214:217], v250 offset:6144
	ds_read_b128 v[218:221], v250 offset:7168
	global_load_lds_dwordx4 v162, s[66:67]
	s_mov_b32 m0, s80
	s_nop 0
	global_load_lds_dwordx4 v164, s[66:67]
	s_sub_u32 s66, s66, 0x7ff80
	s_subb_u32 s67, s67, 0
	s_add_i32 m0, s100, s77
	s_nop 0
	global_load_lds_dwordx4 v162, s[66:67]
	s_add_i32 m0, m0, 0x2000
	s_nop 0
	global_load_lds_dwordx4 v164, s[66:67]
	s_waitcnt vmcnt(10)
	s_waitcnt lgkmcnt(0)
	s_setprio 1
	s_waitcnt lgkmcnt(0)
	v_mfma_f32_16x16x32_bf16 v[122:125], v[130:133], v[176:179], v[122:125]
	v_mfma_f32_16x16x32_bf16 v[58:61], v[138:141], v[176:179], v[58:61]
	v_mfma_f32_16x16x32_bf16 v[114:117], v[130:133], v[184:187], v[114:117]
	v_mfma_f32_16x16x32_bf16 v[50:53], v[138:141], v[184:187], v[50:53]
	s_barrier
; #define PG8_STAGE(bufoff, gbase, voff) do { _Pragma("unroll") for (int _i = 0; _i < 2; ++_i) \
;         __builtin_amdgcn_global_load_lds((const unsigned*)((const char*)(gbase) + (voff)[_i]), (PG8_LAS unsigned*)(lds + (bufoff) + ldsw + _i * 8192), 16, 0, 0); } while (0)
; #define PG8_LDA(dst, b, h) do { _Pragma("unroll") for (int m = 0; m < 4; ++m) _Pragma("unroll") for (int k = 0; k < 2; ++k) dst[m][k] = *(const PG8_LAS bf16x8*)(lds + PG8_SA(b, h) + aoff + m * 2048 + k * 1024); } while (0)
; #define PG8_LDB(dst, b, h) do { _Pragma("unroll") for (int n = 0; n < 2; ++n) _Pragma("unroll") for (int k = 0; k < 2; ++k) dst[n][k] = *(const PG8_LAS bf16x8*)(lds + PG8_SB(b, h) + boff + n * 2048 + k * 1024); } while (0)
; template <class Epi, class Sched, bool ALIGN_EPI = false, bool SP2 = false>
; __device__ __forceinline__ void gemm_phase(PG8_LAS unsigned char* lds, const Gemm g, const Sched& S, const Epi& E) {
;     ...
;         for (int t = 0; t < nt; t += 2) {
;             const bool last = (t == nt - 2);
;             const char* a1 = cA + (size_t)(t + 1) * kstep;
;             const char* a2 = last ? nA : cA + (size_t)(t + 2) * kstep; const char* b2 = last ? nB : cB + (size_t)(t + 2) * kstep;
;             const char* a3 = a2 + kstep; const char* b3 = b2 + kstep;
;             if (last && has_next) S.a_ready(nxt);
;             if constexpr (SP2) {
;             PG8_LDB(B0, 0, 0); PG8_LDB(B1, 0, 1); PG8_SCHED; PG8_LDA(At, 0, 0); PG8_STAGE(PG8_SA(1, 1), a1 + hstep, voffA);
;             PG8_WAIT_V(8); PG8_WAIT_L(0); PG8_BAR; PG8_MMA(0, 0, At, B0); PG8_MMA(0, 1, At, B1); PG8_BAR; PG8_SCHED;
;             PG8_LDA(At, 0, 1); PG8_STAGE(PG8_SB(0, 0), b2, voffB); PG8_STAGE(PG8_SB(0, 1), b2 + hstep, voffB); PG8_STAGE(PG8_SA(0, 0), a2, voffA);
;             PG8_WAIT_V(8); PG8_WAIT_L(0); PG8_BAR; PG8_MMA(1, 0, At, B0); PG8_MMA(1, 1, At, B1); PG8_BAR; PG8_SCHED;
;             PG8_LDB(B0, 1, 0); PG8_LDB(B1, 1, 1); PG8_SCHED; PG8_LDA(At, 1, 0); PG8_STAGE(PG8_SA(0, 1), a2 + hstep, voffA);
;             PG8_WAIT_V(8); PG8_WAIT_L(0); PG8_BAR; PG8_MMA(0, 0, At, B0); PG8_MMA(0, 1, At, B1); PG8_BAR; PG8_SCHED;
;             PG8_LDA(At, 1, 1); PG8_STAGE(PG8_SB(1, 0), b3, voffB); PG8_STAGE(PG8_SB(1, 1), b3 + hstep, voffB); PG8_STAGE(PG8_SA(1, 0), a3, voffA);
;             PG8_WAIT_V(8); PG8_WAIT_L(0); PG8_BAR; PG8_MMA(1, 0, At, B0); PG8_MMA(1, 1, At, B1); PG8_BAR; PG8_SCHED;
	v_mfma_f32_16x16x32_bf16 v[106:109], v[130:133], v[192:195], v[106:109]
	v_mfma_f32_16x16x32_bf16 v[42:45], v[138:141], v[192:195], v[42:45]
	v_mfma_f32_16x16x32_bf16 v[98:101], v[130:133], v[214:217], v[98:101]
	v_mfma_f32_16x16x32_bf16 v[34:37], v[138:141], v[214:217], v[34:37]
	v_mfma_f32_16x16x32_bf16 v[122:125], v[134:137], v[180:183], v[122:125]
	v_mfma_f32_16x16x32_bf16 v[58:61], v[142:145], v[180:183], v[58:61]
	v_mfma_f32_16x16x32_bf16 v[114:117], v[134:137], v[188:191], v[114:117]
	v_mfma_f32_16x16x32_bf16 v[50:53], v[142:145], v[188:191], v[50:53]
	v_mfma_f32_16x16x32_bf16 v[106:109], v[134:137], v[210:213], v[106:109]
	v_mfma_f32_16x16x32_bf16 v[42:45], v[142:145], v[210:213], v[42:45]
	v_mfma_f32_16x16x32_bf16 v[98:101], v[134:137], v[218:221], v[98:101]
	v_mfma_f32_16x16x32_bf16 v[34:37], v[142:145], v[218:221], v[34:37]
	s_setprio 0
	s_setprio 1
	v_mfma_f32_16x16x32_bf16 v[126:129], v[146:149], v[176:179], v[126:129]
	v_mfma_f32_16x16x32_bf16 v[62:65], v[154:157], v[176:179], v[62:65]
	v_mfma_f32_16x16x32_bf16 v[118:121], v[146:149], v[184:187], v[118:121]
	v_mfma_f32_16x16x32_bf16 v[54:57], v[154:157], v[184:187], v[54:57]
	v_mfma_f32_16x16x32_bf16 v[110:113], v[146:149], v[192:195], v[110:113]
	v_mfma_f32_16x16x32_bf16 v[46:49], v[154:157], v[192:195], v[46:49]
	v_mfma_f32_16x16x32_bf16 v[102:105], v[146:149], v[214:217], v[102:105]
	v_mfma_f32_16x16x32_bf16 v[38:41], v[154:157], v[214:217], v[38:41]
	v_mfma_f32_16x16x32_bf16 v[126:129], v[150:153], v[180:183], v[126:129]
	v_mfma_f32_16x16x32_bf16 v[62:65], v[158:161], v[180:183], v[62:65]
	v_mfma_f32_16x16x32_bf16 v[118:121], v[150:153], v[188:191], v[118:121]
	v_mfma_f32_16x16x32_bf16 v[54:57], v[158:161], v[188:191], v[54:57]
	v_mfma_f32_16x16x32_bf16 v[110:113], v[150:153], v[210:213], v[110:113]
	v_mfma_f32_16x16x32_bf16 v[46:49], v[158:161], v[210:213], v[46:49]
	v_mfma_f32_16x16x32_bf16 v[102:105], v[150:153], v[218:221], v[102:105]
	v_mfma_f32_16x16x32_bf16 v[38:41], v[158:161], v[218:221], v[38:41]
	s_setprio 0
	s_barrier
	s_add_i32 s61, s61, s76
	s_mov_b32 m0, s61
	ds_read_b128 v[176:179], v208 offset:49152
	ds_read_b128 v[180:183], v208 offset:50176
	ds_read_b128 v[184:187], v208 offset:51200
	ds_read_b128 v[188:191], v208 offset:52224
	ds_read_b128 v[192:195], v208 offset:53248
	ds_read_b128 v[210:213], v208 offset:54272
	ds_read_b128 v[214:217], v208 offset:55296
	ds_read_b128 v[218:221], v208 offset:56320
	s_add_u32 s62, s62, 0x80
	s_addc_u32 s63, s63, 0
	global_load_lds_dwordx4 v0, s[62:63]
	s_add_i32 m0, s61, 0x2000
	s_add_i32 s61, s85, s76
	global_load_lds_dwordx4 v166, s[62:63]
	s_add_u32 s62, s62, 0x80000
	s_addc_u32 s63, s63, 0
	s_mov_b32 m0, s61
	s_nop 0
	global_load_lds_dwordx4 v0, s[62:63]
	s_add_i32 m0, s61, 0x2000
	s_nop 0
	global_load_lds_dwordx4 v166, s[62:63]
	s_waitcnt vmcnt(8)
	s_waitcnt lgkmcnt(0)
	s_setprio 1
	s_waitcnt lgkmcnt(0)
	v_mfma_f32_16x16x32_bf16 v[90:93], v[130:133], v[176:179], v[90:93]
	v_mfma_f32_16x16x32_bf16 v[26:29], v[138:141], v[176:179], v[26:29]
	v_mfma_f32_16x16x32_bf16 v[82:85], v[130:133], v[184:187], v[82:85]
	v_mfma_f32_16x16x32_bf16 v[18:21], v[138:141], v[184:187], v[18:21]
	s_barrier
	v_mfma_f32_16x16x32_bf16 v[74:77], v[130:133], v[192:195], v[74:77]
	v_mfma_f32_16x16x32_bf16 v[10:13], v[138:141], v[192:195], v[10:13]
	v_mfma_f32_16x16x32_bf16 v[66:69], v[130:133], v[214:217], v[66:69]
	v_mfma_f32_16x16x32_bf16 v[2:5], v[138:141], v[214:217], v[2:5]
	v_mfma_f32_16x16x32_bf16 v[90:93], v[134:137], v[180:183], v[90:93]
	v_mfma_f32_16x16x32_bf16 v[26:29], v[142:145], v[180:183], v[26:29]
	v_mfma_f32_16x16x32_bf16 v[82:85], v[134:137], v[188:191], v[82:85]
	v_mfma_f32_16x16x32_bf16 v[18:21], v[142:145], v[188:191], v[18:21]
	v_mfma_f32_16x16x32_bf16 v[74:77], v[134:137], v[210:213], v[74:77]
	v_mfma_f32_16x16x32_bf16 v[10:13], v[142:145], v[210:213], v[10:13]
	v_mfma_f32_16x16x32_bf16 v[66:69], v[134:137], v[218:221], v[66:69]
	v_mfma_f32_16x16x32_bf16 v[2:5], v[142:145], v[218:221], v[2:5]
	s_setprio 0
	s_setprio 1
	v_mfma_f32_16x16x32_bf16 v[94:97], v[146:149], v[176:179], v[94:97]
	v_mfma_f32_16x16x32_bf16 v[30:33], v[154:157], v[176:179], v[30:33]
	v_mfma_f32_16x16x32_bf16 v[86:89], v[146:149], v[184:187], v[86:89]
	v_mfma_f32_16x16x32_bf16 v[22:25], v[154:157], v[184:187], v[22:25]
	v_mfma_f32_16x16x32_bf16 v[78:81], v[146:149], v[192:195], v[78:81]
	v_mfma_f32_16x16x32_bf16 v[14:17], v[154:157], v[192:195], v[14:17]
	v_mfma_f32_16x16x32_bf16 v[70:73], v[146:149], v[214:217], v[70:73]
	v_mfma_f32_16x16x32_bf16 v[6:9], v[154:157], v[214:217], v[6:9]
	v_mfma_f32_16x16x32_bf16 v[94:97], v[150:153], v[180:183], v[94:97]
	v_mfma_f32_16x16x32_bf16 v[30:33], v[158:161], v[180:183], v[30:33]
	v_mfma_f32_16x16x32_bf16 v[86:89], v[150:153], v[188:191], v[86:89]
	v_mfma_f32_16x16x32_bf16 v[22:25], v[158:161], v[188:191], v[22:25]
	v_mfma_f32_16x16x32_bf16 v[78:81], v[150:153], v[210:213], v[78:81]
	v_mfma_f32_16x16x32_bf16 v[14:17], v[158:161], v[210:213], v[14:17]
	v_mfma_f32_16x16x32_bf16 v[70:73], v[150:153], v[218:221], v[70:73]
	v_mfma_f32_16x16x32_bf16 v[6:9], v[158:161], v[218:221], v[6:9]
	s_setprio 0
	s_barrier
	s_add_i32 s59, s59, 2
	s_mov_b32 s101, s100
	s_mov_b32 s100, vcc_hi
	s_add_u32 s64, s64, 0x100
	s_addc_u32 s65, s65, 0
	s_add_u32 s51, s51, 0x100
	s_addc_u32 s53, s53, 0
	s_cmp_gt_u32 s59, 29
	s_cbranch_scc0 .LBB0_1423
	s_and_b64 vcc, exec, s[48:49]
	s_cbranch_vccz .LBB0_1426
	s_barrier
